# rowpass (post-FFN mode): second raw load and three of the four x loads issued with the first raw load instead of after two full waits
# baseline (speedup 1.0000x reference)
.LBB0_48:
	s_or_b64 exec, exec, s[34:35]
	v_cmp_lt_i32_e32 vcc, s33, v104
	v_mov_b64_e32 v[88:89], v[104:105]
	v_mov_b64_e32 v[90:91], v[114:115]
	s_and_saveexec_b64 s[34:35], vcc
	s_mov_b32 s4, 0x800000
	v_add_u32_e32 v88, 0xffffc000, v104
	v_mov_b32_e32 v89, v185
	v_lshlrev_b64 v[88:89], 12, v[88:89]
	v_lshl_add_u64 v[90:91], s[72:73], 0, v[88:89]
	v_mov_b32_e32 v88, v104
	v_mov_b32_e32 v89, v185
	s_or_b64 exec, exec, s[34:35]
	v_lshlrev_b64 v[124:125], 11, v[88:89]
	v_lshl_add_u64 v[96:97], v[108:109], 0, v[124:125]
	v_lshl_add_u64 v[122:123], v[90:91], 0, v[184:185]
	flat_load_dwordx4 v[90:93], v[96:97]
	flat_load_dwordx4 v[96:99], v[96:97] offset:1024
	global_load_dwordx4 v[100:103], v[122:123], off
	global_load_dwordx4 v[132:135], v[122:123], off offset:2064
	global_load_dwordx4 v[136:139], v[122:123], off offset:2048
	s_waitcnt vmcnt(0) lgkmcnt(0)
	v_lshlrev_b32_e32 v88, 16, v90
	v_and_b32_e32 v89, 0xffff0000, v90
	v_lshlrev_b32_e32 v90, 16, v91
	v_and_b32_e32 v91, 0xffff0000, v91
	v_pk_mul_f32 v[148:149], v[88:89], v[88:89]
	v_pk_mul_f32 v[150:151], v[90:91], v[90:91]
	v_add_f32_e32 v119, v148, v149
	v_lshlrev_b32_e32 v94, 16, v92
	v_and_b32_e32 v95, 0xffff0000, v92
	v_add_f32_e32 v119, v119, v150
	v_pk_mul_f32 v[152:153], v[94:95], v[94:95]
	v_add_f32_e32 v119, v151, v119
	v_lshlrev_b32_e32 v92, 16, v93
	v_and_b32_e32 v93, 0xffff0000, v93
	v_add_f32_e32 v119, v152, v119
	v_pk_mul_f32 v[154:155], v[92:93], v[92:93]
	v_add_f32_e32 v119, v153, v119
	v_add_f32_e32 v119, v154, v119
	v_add_f32_e32 v119, v155, v119
	s_waitcnt vmcnt(0) lgkmcnt(0)
	v_lshlrev_b32_e32 v140, 16, v96
	v_and_b32_e32 v141, 0xffff0000, v96
	v_lshlrev_b32_e32 v142, 16, v97
	v_and_b32_e32 v143, 0xffff0000, v97
	v_lshlrev_b32_e32 v144, 16, v98
	v_and_b32_e32 v145, 0xffff0000, v98
	v_lshlrev_b32_e32 v146, 16, v99
	v_and_b32_e32 v147, 0xffff0000, v99
	global_load_dwordx4 v[96:99], v[122:123], off offset:16
	v_pk_mul_f32 v[156:157], v[140:141], v[140:141]
	v_pk_mul_f32 v[158:159], v[142:143], v[142:143]
	v_add_f32_e32 v119, v156, v119
	v_add_f32_e32 v119, v157, v119
	v_add_f32_e32 v119, v158, v119
	v_pk_mul_f32 v[160:161], v[144:145], v[144:145]
	v_add_f32_e32 v119, v159, v119
	v_add_f32_e32 v119, v160, v119
	v_pk_mul_f32 v[162:163], v[146:147], v[146:147]
	v_add_f32_e32 v119, v161, v119
	v_add_f32_e32 v119, v162, v119
	v_add_f32_e32 v119, v163, v119
	ds_bpermute_b32 v121, v126, v119
	s_waitcnt lgkmcnt(0)
	v_add_f32_e32 v119, v119, v121
	ds_bpermute_b32 v121, v127, v119
	s_waitcnt lgkmcnt(0)
	v_add_f32_e32 v119, v119, v121
	ds_bpermute_b32 v121, v128, v119
	s_waitcnt lgkmcnt(0)
	v_add_f32_e32 v119, v119, v121
	ds_bpermute_b32 v121, v129, v119
	s_waitcnt lgkmcnt(0)
	v_add_f32_e32 v119, v119, v121
	ds_bpermute_b32 v121, v130, v119
	s_waitcnt lgkmcnt(0)
	v_add_f32_e32 v119, v119, v121
	ds_bpermute_b32 v121, v131, v119
	s_waitcnt lgkmcnt(0)
	v_add_f32_e32 v119, v119, v121
	v_fmamk_f32 v119, v119, 0x3a800000, v219
	v_cmp_gt_f32_e32 vcc, s4, v119
	v_mul_f32_e32 v121, 0x4b800000, v119
	s_nop 0
	v_cndmask_b32_e32 v119, v119, v121, vcc
	v_rsq_f32_e32 v119, v119
	s_nop 0
	v_mul_f32_e32 v121, 0x45800000, v119
	v_cndmask_b32_e32 v148, v119, v121, vcc
	v_pk_mul_f32 v[92:93], v[148:149], v[92:93] op_sel_hi:[0,1]
	v_pk_mul_f32 v[92:93], v[26:27], v[92:93]
	v_pk_mul_f32 v[88:89], v[148:149], v[88:89] op_sel_hi:[0,1]
	v_pk_mul_f32 v[88:89], v[0:1], v[88:89]
	v_pk_mul_f32 v[90:91], v[148:149], v[90:91] op_sel_hi:[0,1]
	v_pk_mul_f32 v[94:95], v[148:149], v[94:95] op_sel_hi:[0,1]
	v_pk_mul_f32 v[90:91], v[2:3], v[90:91]
	v_pk_mul_f32 v[94:95], v[24:25], v[94:95]
	v_cndmask_b32_e64 v119, 0, 1, s[28:29]
	v_cmp_ne_u32_e64 s[36:37], 1, v119
	s_andn2_b64 vcc, exec, s[28:29]
	s_waitcnt vmcnt(0)
	v_pk_fma_f32 v[98:99], v[38:39], v[92:93], v[98:99]
	v_pk_mul_f32 v[92:93], v[148:149], v[140:141] op_sel_hi:[0,1]
	v_pk_mul_f32 v[92:93], v[16:17], v[92:93]
	s_waitcnt vmcnt(2)
	v_pk_fma_f32 v[88:89], v[32:33], v[88:89], v[100:101]
	s_waitcnt vmcnt(0)
	v_pk_fma_f32 v[100:101], v[56:57], v[92:93], v[136:137]
	v_pk_mul_f32 v[92:93], v[148:149], v[142:143] op_sel_hi:[0,1]
	v_pk_mul_f32 v[92:93], v[18:19], v[92:93]
	v_pk_fma_f32 v[90:91], v[34:35], v[90:91], v[102:103]
	v_pk_fma_f32 v[96:97], v[36:37], v[94:95], v[96:97]
	v_pk_fma_f32 v[102:103], v[58:59], v[92:93], v[138:139]
	v_pk_mul_f32 v[92:93], v[148:149], v[144:145] op_sel_hi:[0,1]
	v_pk_mul_f32 v[94:95], v[148:149], v[146:147] op_sel_hi:[0,1]
	v_pk_mul_f32 v[92:93], v[20:21], v[92:93]
	v_pk_mul_f32 v[94:95], v[22:23], v[94:95]
	v_pk_fma_f32 v[92:93], v[60:61], v[92:93], v[132:133]
	v_pk_fma_f32 v[94:95], v[62:63], v[94:95], v[134:135]
	s_cbranch_vccnz .LBB0_52
	v_pk_mul_f32 v[72:73], v[88:89], v[88:89]
	v_pk_mul_f32 v[74:75], v[90:91], v[90:91]
	v_add_f32_e32 v72, v72, v73
	v_add_f32_e32 v72, v74, v72
	v_pk_mul_f32 v[84:85], v[96:97], v[96:97]
	v_add_f32_e32 v72, v75, v72
	v_add_f32_e32 v72, v84, v72
	v_pk_mul_f32 v[86:87], v[98:99], v[98:99]
	v_add_f32_e32 v72, v85, v72
	v_add_f32_e32 v72, v86, v72
	v_pk_mul_f32 v[132:133], v[100:101], v[100:101]
	v_add_f32_e32 v72, v87, v72
	v_add_f32_e32 v72, v132, v72
	v_pk_mul_f32 v[134:135], v[102:103], v[102:103]
	v_add_f32_e32 v72, v133, v72
	v_add_f32_e32 v72, v134, v72
	v_pk_mul_f32 v[136:137], v[92:93], v[92:93]
	v_add_f32_e32 v72, v135, v72
	v_add_f32_e32 v72, v136, v72
	v_pk_mul_f32 v[138:139], v[94:95], v[94:95]
	v_add_f32_e32 v72, v137, v72
	v_add_f32_e32 v72, v138, v72
	v_add_f32_e32 v72, v139, v72
	ds_bpermute_b32 v73, v126, v72
	v_add_f32_e32 v74, 1.0, v52
	v_add_f32_e32 v75, 1.0, v53
	v_add_f32_e32 v84, 1.0, v55
	v_add_f32_e32 v85, 1.0, v48
	s_waitcnt lgkmcnt(0)
	v_add_f32_e32 v72, v72, v73
	ds_bpermute_b32 v73, v127, v72
	v_add_f32_e32 v134, 1.0, v78
	s_waitcnt lgkmcnt(0)
	v_add_f32_e32 v72, v72, v73
	ds_bpermute_b32 v73, v128, v72
	s_waitcnt lgkmcnt(0)
	v_add_f32_e32 v72, v72, v73
	ds_bpermute_b32 v73, v129, v72
	s_waitcnt lgkmcnt(0)
	v_add_f32_e32 v72, v72, v73
	ds_bpermute_b32 v73, v130, v72
	s_waitcnt lgkmcnt(0)
	v_add_f32_e32 v72, v72, v73
	ds_bpermute_b32 v73, v131, v72
	s_waitcnt lgkmcnt(0)
	v_add_f32_e32 v72, v72, v73
	v_fmamk_f32 v72, v72, 0x3a800000, v219
	v_mul_f32_e32 v73, 0x4b800000, v72
	v_cmp_gt_f32_e32 vcc, s4, v72
	s_nop 1
	v_cndmask_b32_e32 v72, v72, v73, vcc
	v_rsq_f32_e32 v72, v72
	v_add_f32_e32 v73, 1.0, v54
	v_mul_f32_e32 v86, 0x45800000, v72
	v_cndmask_b32_e32 v86, v72, v86, vcc
	v_mul_f32_e32 v72, v88, v86
	v_mul_f32_e32 v87, v89, v86
	v_mul_f32_e32 v121, v91, v86
	v_mul_f32_e32 v132, v96, v86
	v_mul_f32_e32 v119, v90, v86
	v_mul_f32_e32 v133, v97, v86
	v_mul_f32_e32 v72, v4, v72
	v_mul_f32_e32 v87, v5, v87
	v_mul_f32_e32 v121, v7, v121
	v_mul_f32_e32 v132, v8, v132
	v_mul_f32_e32 v119, v6, v119
	v_mul_f32_e32 v133, v9, v133
	v_fma_f32 v72, v74, v72, v40
	v_fma_f32 v74, v75, v87, v41
	v_fma_f32 v75, v84, v121, v43
	v_fma_f32 v84, v85, v132, v44
	v_add_f32_e32 v85, 1.0, v49
	v_mul_f32_e32 v87, v98, v86
	v_fma_f32 v73, v73, v119, v42
	v_fma_f32 v85, v85, v133, v45
	v_mul_f32_e32 v87, v10, v87
	v_add_f32_e32 v119, 1.0, v50
	v_cvt_pk_bf16_f32 v72, v72, v74
	v_cvt_pk_bf16_f32 v74, v84, v85
	v_mul_f32_e32 v84, v100, v86
	v_fma_f32 v87, v119, v87, v46
	v_mul_f32_e32 v119, v99, v86
	v_mul_f32_e32 v84, v12, v84
	v_add_f32_e32 v85, 1.0, v80
	v_mul_f32_e32 v119, v11, v119
	v_add_f32_e32 v121, 1.0, v51
	v_fma_f32 v84, v85, v84, v64
	v_mul_f32_e32 v85, v101, v86
	v_fma_f32 v119, v121, v119, v47
	v_cvt_pk_bf16_f32 v73, v73, v75
	v_cvt_pk_bf16_f32 v75, v87, v119
	v_mul_f32_e32 v85, v13, v85
	v_add_f32_e32 v87, 1.0, v81
	v_fma_f32 v85, v87, v85, v65
	v_mul_f32_e32 v87, v102, v86
	v_mul_f32_e32 v87, v14, v87
	v_add_f32_e32 v119, 1.0, v82
	v_fma_f32 v87, v119, v87, v66
	v_mul_f32_e32 v119, v103, v86
	v_mul_f32_e32 v119, v15, v119
	v_add_f32_e32 v121, 1.0, v83
	v_fma_f32 v119, v121, v119, v67
	v_mul_f32_e32 v121, v92, v86
	v_mul_f32_e32 v121, v28, v121
	v_add_f32_e32 v132, 1.0, v76
	v_fma_f32 v121, v132, v121, v68
	v_mul_f32_e32 v132, v93, v86
	v_mul_f32_e32 v132, v29, v132
	v_add_f32_e32 v133, 1.0, v77
	v_fma_f32 v132, v133, v132, v69
	v_mul_f32_e32 v133, v94, v86
	v_mul_f32_e32 v133, v30, v133
	v_mul_f32_e32 v86, v95, v86
	v_fma_f32 v133, v134, v133, v70
	v_mul_f32_e32 v86, v31, v86
	v_add_f32_e32 v134, 1.0, v79
	v_fma_f32 v134, v134, v86, v71
	v_cvt_pk_bf16_f32 v84, v84, v85
	v_cvt_pk_bf16_f32 v85, v87, v119
	v_cvt_pk_bf16_f32 v86, v121, v132
	v_cvt_pk_bf16_f32 v87, v133, v134
